# retention: QK/cross MFMA fragment reads one step ahead; state-update fragment reads paired; gain vector hoisted out of rmsnorm loops; gate SG loads batched
# speedup vs baseline: 1.0100x; 1.0100x over previous
.LBB0_2435:
	v_and_b32_e32 v217, 31, v34
	v_or_b32_e32 v236, s0, v217
	v_or_b32_e32 v225, s33, v217
	v_mul_u32_u24_e32 v32, 0x210, v236
	v_bfe_u32 v238, v34, 5, 1
	v_mul_lo_u32 v33, v225, s90
	s_cmp_lt_u32 s33, s27
	v_add_u32_e32 v237, 0, v33
	v_lshlrev_b32_e32 v222, 4, v238
	v_add_u32_e32 v223, s17, v32
	v_cndmask_b32_e64 v32, 0, 1, s[94:95]
	s_cselect_b64 s[84:85], -1, 0
	s_cmp_ge_u32 s33, s27
	v_add_u32_e32 v157, 0, v222
	v_add_u32_e32 v224, v237, v222
	v_cmp_ne_u32_e64 s[56:57], 1, v32
	s_cbranch_scc1 .LBB0_2438
	ds_read_b128 v[32:35], v224
	s_and_b64 vcc, exec, s[56:57]
	s_cbranch_vccnz .LBB0_2439
	v_or_b32_e32 v36, s88, v217
	v_mad_u32_u24 v44, v36, s90, v157
	s_waitcnt vmcnt(8)
	ds_read_b128 v[36:39], v44 offset:34816
	ds_read_b128 v[40:43], v44 offset:34848
	ds_read_b128 v[126:129], v224 offset:32
	s_waitcnt lgkmcnt(2)
	v_mfma_f32_32x32x16_bf16 v[64:79], v[36:39], v[32:35], 0
	ds_read_b128 v[36:39], v44 offset:34880
	ds_read_b128 v[130:133], v224 offset:64
	s_waitcnt lgkmcnt(2)
	v_mfma_f32_32x32x16_bf16 v[64:79], v[40:43], v[126:129], v[64:79]
	ds_read_b128 v[40:43], v44 offset:34912
	ds_read_b128 v[134:137], v224 offset:96
	s_waitcnt lgkmcnt(2)
	v_mfma_f32_32x32x16_bf16 v[64:79], v[36:39], v[130:133], v[64:79]
	ds_read_b128 v[36:39], v44 offset:34944
	ds_read_b128 v[138:141], v224 offset:128
	s_waitcnt lgkmcnt(2)
	v_mfma_f32_32x32x16_bf16 v[64:79], v[40:43], v[134:137], v[64:79]
	ds_read_b128 v[40:43], v44 offset:34976
	ds_read_b128 v[142:145], v224 offset:160
	s_waitcnt lgkmcnt(2)
	v_mfma_f32_32x32x16_bf16 v[64:79], v[36:39], v[138:141], v[64:79]
	ds_read_b128 v[36:39], v44 offset:35008
	ds_read_b128 v[146:149], v224 offset:192
	s_waitcnt lgkmcnt(2)
	v_mfma_f32_32x32x16_bf16 v[64:79], v[40:43], v[142:145], v[64:79]
	ds_read_b128 v[40:43], v44 offset:35040
	ds_read_b128 v[150:153], v224 offset:224
	s_waitcnt lgkmcnt(2)
	v_mfma_f32_32x32x16_bf16 v[64:79], v[36:39], v[146:149], v[64:79]
	s_waitcnt lgkmcnt(0)
	v_mfma_f32_32x32x16_bf16 v[64:79], v[40:43], v[150:153], v[64:79]
	s_andn2_b64 vcc, exec, s[10:11]
	s_mov_b64 s[38:39], -1
	s_cbranch_vccnz .LBB0_2441
	s_branch .LBB0_2440

.LBB0_2441:
	s_andn2_b64 vcc, exec, s[38:39]
	s_cbranch_vccnz .LBB0_2443
	v_or_b32_e32 v36, s88, v217
	v_mad_u32_u24 v44, v36, s90, v157
	s_waitcnt vmcnt(8)
	ds_read_b128 v[36:39], v44 offset:43520
	ds_read_b128 v[40:43], v44 offset:43552
	ds_read_b128 v[126:129], v224 offset:32
	s_waitcnt lgkmcnt(2)
	v_mfma_f32_32x32x16_bf16 v[48:63], v[36:39], v[32:35], 0
	ds_read_b128 v[36:39], v44 offset:43584
	ds_read_b128 v[130:133], v224 offset:64
	s_waitcnt lgkmcnt(2)
	v_mfma_f32_32x32x16_bf16 v[48:63], v[40:43], v[126:129], v[48:63]
	ds_read_b128 v[40:43], v44 offset:43616
	ds_read_b128 v[134:137], v224 offset:96
	s_waitcnt lgkmcnt(2)
	v_mfma_f32_32x32x16_bf16 v[48:63], v[36:39], v[130:133], v[48:63]
	ds_read_b128 v[36:39], v44 offset:43648
	ds_read_b128 v[138:141], v224 offset:128
	s_waitcnt lgkmcnt(2)
	v_mfma_f32_32x32x16_bf16 v[48:63], v[40:43], v[134:137], v[48:63]
	ds_read_b128 v[40:43], v44 offset:43680
	ds_read_b128 v[142:145], v224 offset:160
	s_waitcnt lgkmcnt(2)
	v_mfma_f32_32x32x16_bf16 v[48:63], v[36:39], v[138:141], v[48:63]
	ds_read_b128 v[36:39], v44 offset:43712
	ds_read_b128 v[146:149], v224 offset:192
	s_waitcnt lgkmcnt(2)
	v_mfma_f32_32x32x16_bf16 v[48:63], v[40:43], v[142:145], v[48:63]
	ds_read_b128 v[40:43], v44 offset:43744
	ds_read_b128 v[150:153], v224 offset:224
	s_waitcnt lgkmcnt(2)
	v_mfma_f32_32x32x16_bf16 v[48:63], v[36:39], v[146:149], v[48:63]
	s_waitcnt lgkmcnt(0)
	v_mfma_f32_32x32x16_bf16 v[48:63], v[40:43], v[150:153], v[48:63]
	s_branch .LBB0_2444

.LBB0_2444:
	v_add_u32_e32 v245, v223, v222
	ds_read_b128 v[36:39], v245
	ds_read_b128 v[158:161], v245 offset:32
	s_waitcnt lgkmcnt(1)
	v_mfma_f32_32x32x16_bf16 v[32:47], v[36:39], v[32:35], 0
	s_waitcnt vmcnt(8) lgkmcnt(0)
	v_mfma_f32_32x32x16_bf16 v[32:47], v[158:161], v[126:129], v[32:47]
	ds_read_b128 v[126:129], v245 offset:64
	ds_read_b128 v[158:161], v245 offset:96
	s_waitcnt lgkmcnt(1)
	v_mfma_f32_32x32x16_bf16 v[32:47], v[126:129], v[130:133], v[32:47]
	ds_read_b128 v[126:129], v245 offset:128
	s_waitcnt lgkmcnt(1)
	v_mfma_f32_32x32x16_bf16 v[32:47], v[158:161], v[134:137], v[32:47]
	ds_read_b128 v[158:161], v245 offset:160
	s_waitcnt lgkmcnt(1)
	v_mfma_f32_32x32x16_bf16 v[32:47], v[126:129], v[138:141], v[32:47]
	ds_read_b128 v[126:129], v245 offset:192
	s_waitcnt lgkmcnt(1)
	v_mfma_f32_32x32x16_bf16 v[32:47], v[158:161], v[142:145], v[32:47]
	ds_read_b128 v[158:161], v245 offset:224
	s_waitcnt lgkmcnt(1)
	v_mfma_f32_32x32x16_bf16 v[32:47], v[126:129], v[146:149], v[32:47]
	s_waitcnt lgkmcnt(0)
	v_mfma_f32_32x32x16_bf16 v[32:47], v[158:161], v[150:153], v[32:47]

.LBB0_2465:
	v_cndmask_b32_e64 v126, 0, 1, s[84:85]
	v_cmp_ne_u32_e64 s[54:55], 1, v126
	s_andn2_b64 vcc, exec, s[84:85]
	s_cbranch_vccnz .LBB0_2473
	ds_read_b128 v[126:129], v224
	v_or_b32_e32 v130, s88, v217
	s_and_b64 vcc, exec, s[56:57]
	v_mad_u32_u24 v239, v130, s90, v157
	s_cbranch_vccnz .LBB0_2468
	ds_read_b128 v[130:133], v239 offset:34816
	ds_read_b128 v[138:141], v239 offset:34848
	ds_read_b128 v[142:145], v224 offset:32
	s_waitcnt lgkmcnt(2)
	v_mfma_f32_32x32x16_bf16 v[64:79], v[130:133], v[126:129], v[64:79]
	ds_read_b128 v[130:133], v239 offset:34880
	ds_read_b128 v[134:137], v224 offset:64
	s_waitcnt lgkmcnt(2)
	v_mfma_f32_32x32x16_bf16 v[64:79], v[138:141], v[142:145], v[64:79]
	ds_read_b128 v[138:141], v239 offset:34912
	ds_read_b128 v[142:145], v224 offset:96
	s_waitcnt lgkmcnt(2)
	v_mfma_f32_32x32x16_bf16 v[64:79], v[130:133], v[134:137], v[64:79]
	ds_read_b128 v[130:133], v239 offset:34944
	ds_read_b128 v[134:137], v224 offset:128
	s_waitcnt lgkmcnt(2)
	v_mfma_f32_32x32x16_bf16 v[64:79], v[138:141], v[142:145], v[64:79]
	ds_read_b128 v[138:141], v239 offset:34976
	ds_read_b128 v[142:145], v224 offset:160
	s_waitcnt lgkmcnt(2)
	v_mfma_f32_32x32x16_bf16 v[64:79], v[130:133], v[134:137], v[64:79]
	ds_read_b128 v[130:133], v239 offset:35008
	ds_read_b128 v[134:137], v224 offset:192
	s_waitcnt lgkmcnt(2)
	v_mfma_f32_32x32x16_bf16 v[64:79], v[138:141], v[142:145], v[64:79]
	ds_read_b128 v[138:141], v239 offset:35040
	ds_read_b128 v[142:145], v224 offset:224
	s_waitcnt lgkmcnt(2)
	v_mfma_f32_32x32x16_bf16 v[64:79], v[130:133], v[134:137], v[64:79]
	s_waitcnt lgkmcnt(0)
	v_mfma_f32_32x32x16_bf16 v[64:79], v[138:141], v[142:145], v[64:79]

.LBB0_2471:
	s_waitcnt lgkmcnt(0)
	ds_read_b128 v[158:161], v239 offset:43520
	ds_read_b128 v[154:157], v239 offset:43552
	ds_read_b128 v[142:145], v224 offset:32
	s_waitcnt lgkmcnt(2)
	v_mfma_f32_32x32x16_bf16 v[48:63], v[158:161], v[126:129], v[48:63]
	ds_read_b128 v[158:161], v239 offset:43584
	ds_read_b128 v[150:153], v224 offset:64
	s_waitcnt lgkmcnt(2)
	v_mfma_f32_32x32x16_bf16 v[48:63], v[154:157], v[142:145], v[48:63]
	ds_read_b128 v[154:157], v239 offset:43616
	ds_read_b128 v[134:137], v224 offset:96
	s_waitcnt lgkmcnt(2)
	v_mfma_f32_32x32x16_bf16 v[48:63], v[158:161], v[150:153], v[48:63]
	ds_read_b128 v[158:161], v239 offset:43648
	ds_read_b128 v[146:149], v224 offset:128
	s_waitcnt lgkmcnt(2)
	v_mfma_f32_32x32x16_bf16 v[48:63], v[154:157], v[134:137], v[48:63]
	ds_read_b128 v[154:157], v239 offset:43680
	ds_read_b128 v[130:133], v224 offset:160
	s_waitcnt lgkmcnt(2)
	v_mfma_f32_32x32x16_bf16 v[48:63], v[158:161], v[146:149], v[48:63]
	ds_read_b128 v[158:161], v239 offset:43712
	ds_read_b128 v[138:141], v224 offset:192
	s_waitcnt lgkmcnt(2)
	v_mfma_f32_32x32x16_bf16 v[48:63], v[154:157], v[130:133], v[48:63]
	ds_read_b128 v[154:157], v224 offset:224
	s_waitcnt lgkmcnt(1)
	v_mfma_f32_32x32x16_bf16 v[48:63], v[158:161], v[138:141], v[48:63]
	ds_read_b128 v[158:161], v239 offset:43744
	s_waitcnt lgkmcnt(0)
	v_mfma_f32_32x32x16_bf16 v[48:63], v[158:161], v[154:157], v[48:63]
.LBB0_2472:
	v_add_u32_e32 v223, v223, v222
	ds_read_b128 v[158:161], v223 offset:256
	s_waitcnt lgkmcnt(0)
	v_mfma_f32_32x32x16_bf16 v[32:47], v[158:161], v[126:129], v[32:47]
	ds_read_b128 v[126:129], v223 offset:288
	ds_read_b128 v[158:161], v223 offset:320
	s_waitcnt lgkmcnt(1)
	v_mfma_f32_32x32x16_bf16 v[32:47], v[126:129], v[142:145], v[32:47]
	ds_read_b128 v[126:129], v223 offset:352
	s_waitcnt lgkmcnt(1)
	v_mfma_f32_32x32x16_bf16 v[32:47], v[158:161], v[150:153], v[32:47]
	ds_read_b128 v[158:161], v223 offset:384
	s_waitcnt lgkmcnt(1)
	v_mfma_f32_32x32x16_bf16 v[32:47], v[126:129], v[134:137], v[32:47]
	ds_read_b128 v[126:129], v223 offset:416
	s_waitcnt lgkmcnt(1)
	v_mfma_f32_32x32x16_bf16 v[32:47], v[158:161], v[146:149], v[32:47]
	ds_read_b128 v[158:161], v223 offset:448
	s_waitcnt lgkmcnt(1)
	v_mfma_f32_32x32x16_bf16 v[32:47], v[126:129], v[130:133], v[32:47]
	ds_read_b128 v[126:129], v223 offset:480
	s_waitcnt lgkmcnt(1)
	v_mfma_f32_32x32x16_bf16 v[32:47], v[158:161], v[138:141], v[32:47]
	s_waitcnt lgkmcnt(0)
	v_mfma_f32_32x32x16_bf16 v[32:47], v[126:129], v[154:157], v[32:47]

.LBB0_2502:
	v_cvt_f32_ubyte0_e32 v32, s27
	v_mul_f32_e32 v32, v215, v32
	v_exp_f32_e32 v38, v32
	v_mov_b32_e32 v32, s91
	v_mad_u32_u24 v32, v217, s90, v32
	v_add_u32_e32 v32, v32, v222
	ds_read_b128 v[34:37], v32
	v_pk_mul_f32 v[14:15], v[14:15], v[38:39] op_sel_hi:[1,0]
	v_pk_mul_f32 v[12:13], v[12:13], v[38:39] op_sel_hi:[1,0]
	v_pk_mul_f32 v[10:11], v[10:11], v[38:39] op_sel_hi:[1,0]
	v_pk_mul_f32 v[8:9], v[8:9], v[38:39] op_sel_hi:[1,0]
	v_pk_mul_f32 v[6:7], v[6:7], v[38:39] op_sel_hi:[1,0]
	v_pk_mul_f32 v[4:5], v[4:5], v[38:39] op_sel_hi:[1,0]
	v_pk_mul_f32 v[2:3], v[2:3], v[38:39] op_sel_hi:[1,0]
	v_pk_mul_f32 v[0:1], v[0:1], v[38:39] op_sel_hi:[1,0]
	v_pk_mul_f32 v[30:31], v[30:31], v[38:39] op_sel_hi:[1,0]
	v_pk_mul_f32 v[28:29], v[28:29], v[38:39] op_sel_hi:[1,0]
	s_waitcnt vmcnt(7) lgkmcnt(0)
	v_mfma_f32_32x32x16_bf16 v[0:15], v[154:157], v[34:37], v[0:15]
	ds_read_b128 v[34:37], v32 offset:8704
	v_mul_f32_e64 v26, v26, v38
	v_mul_f32_e64 v27, v27, v38
	v_mul_f32_e64 v24, v24, v38
	v_mul_f32_e64 v25, v25, v38
	v_pk_mul_f32 v[22:23], v[22:23], v[38:39] op_sel_hi:[1,0]
	v_pk_mul_f32 v[20:21], v[20:21], v[38:39] op_sel_hi:[1,0]
	v_pk_mul_f32 v[18:19], v[18:19], v[38:39] op_sel_hi:[1,0]
	v_pk_mul_f32 v[16:17], v[16:17], v[38:39] op_sel_hi:[1,0]
	v_cndmask_b32_e64 v33, 0, 1, s[66:67]
	v_cmp_ne_u32_e64 s[54:55], 1, v33
	s_waitcnt lgkmcnt(0)
	v_mfma_f32_32x32x16_bf16 v[16:31], v[154:157], v[34:37], v[16:31]
	s_andn2_b64 vcc, exec, s[66:67]
	s_cbranch_vccnz .LBB0_2519
	ds_read_b128 v[34:37], v32 offset:32
	ds_read_b128 v[40:43], v32 offset:8736
	s_waitcnt vmcnt(6) lgkmcnt(1)
	v_mfma_f32_32x32x16_bf16 v[0:15], v[150:153], v[34:37], v[0:15]
	s_waitcnt lgkmcnt(0)
	v_mfma_f32_32x32x16_bf16 v[16:31], v[150:153], v[40:43], v[16:31]
	s_and_b64 vcc, exec, s[54:55]
	s_cbranch_vccz .LBB0_2520

.LBB0_2505:
	ds_read_b128 v[34:37], v32 offset:96
	ds_read_b128 v[40:43], v32 offset:8800
	s_waitcnt vmcnt(4) lgkmcnt(1)
	v_mfma_f32_32x32x16_bf16 v[0:15], v[142:145], v[34:37], v[0:15]
	s_waitcnt lgkmcnt(0)
	v_mfma_f32_32x32x16_bf16 v[16:31], v[142:145], v[40:43], v[16:31]
	s_and_b64 vcc, exec, s[54:55]
	s_cbranch_vccz .LBB0_2522

.LBB0_2507:
	ds_read_b128 v[34:37], v32 offset:160
	ds_read_b128 v[40:43], v32 offset:8864
	s_waitcnt vmcnt(2) lgkmcnt(1)
	v_mfma_f32_32x32x16_bf16 v[0:15], v[134:137], v[34:37], v[0:15]
	s_waitcnt lgkmcnt(0)
	v_mfma_f32_32x32x16_bf16 v[16:31], v[134:137], v[40:43], v[16:31]
	s_and_b64 vcc, exec, s[54:55]
	s_cbranch_vccz .LBB0_2524

.LBB0_2509:
	ds_read_b128 v[34:37], v32 offset:224
	ds_read_b128 v[40:43], v32 offset:8928
	s_waitcnt vmcnt(0) lgkmcnt(1)
	v_mfma_f32_32x32x16_bf16 v[0:15], v[126:129], v[34:37], v[0:15]
	s_waitcnt lgkmcnt(0)
	v_mfma_f32_32x32x16_bf16 v[16:31], v[126:129], v[40:43], v[16:31]

.LBB0_2520:
	ds_read_b128 v[34:37], v32 offset:64
	ds_read_b128 v[40:43], v32 offset:8768
	s_waitcnt vmcnt(5) lgkmcnt(1)
	v_mfma_f32_32x32x16_bf16 v[0:15], v[146:149], v[34:37], v[0:15]
	s_waitcnt lgkmcnt(0)
	v_mfma_f32_32x32x16_bf16 v[16:31], v[146:149], v[40:43], v[16:31]
	s_and_b64 vcc, exec, s[54:55]
	s_cbranch_vccz .LBB0_2505

.LBB0_2522:
	ds_read_b128 v[34:37], v32 offset:128
	ds_read_b128 v[40:43], v32 offset:8832
	s_waitcnt vmcnt(3) lgkmcnt(1)
	v_mfma_f32_32x32x16_bf16 v[0:15], v[138:141], v[34:37], v[0:15]
	s_waitcnt lgkmcnt(0)
	v_mfma_f32_32x32x16_bf16 v[16:31], v[138:141], v[40:43], v[16:31]
	s_and_b64 vcc, exec, s[54:55]
	s_cbranch_vccz .LBB0_2507

.LBB0_2524:
	ds_read_b128 v[34:37], v32 offset:192
	ds_read_b128 v[40:43], v32 offset:8896
	s_waitcnt vmcnt(1) lgkmcnt(1)
	v_mfma_f32_32x32x16_bf16 v[0:15], v[130:133], v[34:37], v[0:15]
	s_waitcnt lgkmcnt(0)
	v_mfma_f32_32x32x16_bf16 v[16:31], v[130:133], v[40:43], v[16:31]
	s_and_b64 vcc, exec, s[54:55]
	s_cbranch_vccz .LBB0_2509
	s_branch .LBB0_2510

.LBB0_2727:
	s_add_i32 s7, s18, s14
	s_cmpk_lt_i32 s7, 0x4100
	s_cselect_b32 s42, s7, s18
	s_ashr_i32 s19, s18, 31
	s_lshl_b64 s[12:13], s[18:19], 12
	v_lshl_add_u64 v[0:1], v[16:17], 0, s[12:13]
	global_load_dwordx4 v[22:25], v[0:1], off offset:48
	global_load_dwordx4 v[26:29], v[0:1], off offset:32
	global_load_dwordx4 v[30:33], v[0:1], off offset:16
	global_load_dwordx4 v[34:37], v[0:1], off
	s_ashr_i32 s43, s42, 31
	s_lshl_b64 s[4:5], s[42:43], 12
	v_lshl_add_u64 v[12:13], v[16:17], 0, s[4:5]
	global_load_dwordx4 v[0:3], v[12:13], off offset:48
	global_load_dwordx4 v[4:7], v[12:13], off offset:32
	global_load_dwordx4 v[8:11], v[12:13], off offset:16
	s_nop 0
	global_load_dwordx4 v[12:15], v[12:13], off
	s_waitcnt vmcnt(40)
	v_mov_b32_e32 v82, v81
	s_cmp_eq_u32 s18, s42
	s_mov_b32 s18, 0xf800000
	v_mov_b32_e32 v55, v81
	s_waitcnt vmcnt(7)
	v_and_b32_e32 v52, 0xffff0000, v22
	s_waitcnt vmcnt(6)
	v_and_b32_e32 v63, 0xffff0000, v26
	s_waitcnt vmcnt(5)
	v_and_b32_e32 v71, 0xffff0000, v30
	s_waitcnt vmcnt(4)
	v_and_b32_e32 v79, 0xffff0000, v34
	v_and_b32_e32 v77, 0xffff0000, v35
	v_lshlrev_b32_e32 v80, 16, v34
	v_mul_f32_e32 v34, v79, v79
	v_lshlrev_b32_e32 v78, 16, v35
	v_mul_f32_e32 v35, v77, v77
	v_fmac_f32_e32 v34, v80, v80
	v_fmac_f32_e32 v35, v78, v78
	v_and_b32_e32 v75, 0xffff0000, v36
	v_add_f32_e32 v34, v34, v35
	v_lshlrev_b32_e32 v76, 16, v36
	v_mul_f32_e32 v35, v75, v75
	v_fmac_f32_e32 v35, v76, v76
	v_and_b32_e32 v73, 0xffff0000, v37
	v_add_f32_e32 v34, v34, v35
	v_lshlrev_b32_e32 v74, 16, v37
	v_mul_f32_e32 v35, v73, v73
	v_fmac_f32_e32 v35, v74, v74
	v_lshlrev_b32_e32 v72, 16, v30
	v_mul_f32_e32 v30, v71, v71
	v_and_b32_e32 v69, 0xffff0000, v31
	v_add_f32_e32 v34, v34, v35
	v_fmac_f32_e32 v30, v72, v72
	v_lshlrev_b32_e32 v70, 16, v31
	v_mul_f32_e32 v31, v69, v69
	v_add_f32_e32 v30, v34, v30
	v_fmac_f32_e32 v31, v70, v70
	v_and_b32_e32 v67, 0xffff0000, v32
	v_add_f32_e32 v30, v30, v31
	v_lshlrev_b32_e32 v68, 16, v32
	v_mul_f32_e32 v31, v67, v67
	v_fmac_f32_e32 v31, v68, v68
	v_and_b32_e32 v65, 0xffff0000, v33
	v_add_f32_e32 v30, v30, v31
	v_lshlrev_b32_e32 v66, 16, v33
	v_mul_f32_e32 v31, v65, v65
	v_fmac_f32_e32 v31, v66, v66
	v_lshlrev_b32_e32 v64, 16, v26
	v_mul_f32_e32 v26, v63, v63
	v_and_b32_e32 v60, 0xffff0000, v27
	s_waitcnt vmcnt(0)
	v_and_b32_e32 v46, 0xffff0000, v12
	v_and_b32_e32 v42, 0xffff0000, v13
	v_add_f32_e32 v30, v30, v31
	v_fmac_f32_e32 v26, v64, v64
	v_lshlrev_b32_e32 v61, 16, v27
	v_mul_f32_e32 v27, v60, v60
	v_lshlrev_b32_e32 v47, 16, v12
	v_mul_f32_e32 v12, v46, v46
	v_lshlrev_b32_e32 v43, 16, v13
	v_mul_f32_e32 v13, v42, v42
	v_add_f32_e32 v26, v30, v26
	v_fmac_f32_e32 v27, v61, v61
	v_and_b32_e32 v58, 0xffff0000, v28
	v_fmac_f32_e32 v12, v47, v47
	v_fmac_f32_e32 v13, v43, v43
	v_and_b32_e32 v40, 0xffff0000, v14
	v_add_f32_e32 v26, v26, v27
	v_lshlrev_b32_e32 v59, 16, v28
	v_mul_f32_e32 v27, v58, v58
	v_add_f32_e32 v12, v12, v13
	v_lshlrev_b32_e32 v41, 16, v14
	v_mul_f32_e32 v13, v40, v40
	v_fmac_f32_e32 v27, v59, v59
	v_and_b32_e32 v56, 0xffff0000, v29
	v_fmac_f32_e32 v13, v41, v41
	v_and_b32_e32 v38, 0xffff0000, v15
	v_add_f32_e32 v26, v26, v27
	v_lshlrev_b32_e32 v57, 16, v29
	v_mul_f32_e32 v27, v56, v56
	v_add_f32_e32 v12, v12, v13
	v_lshlrev_b32_e32 v39, 16, v15
	v_mul_f32_e32 v13, v38, v38
	v_and_b32_e32 v36, 0xffff0000, v8
	v_fmac_f32_e32 v27, v57, v57
	v_lshlrev_b32_e32 v53, 16, v22
	v_mul_f32_e32 v22, v52, v52
	v_and_b32_e32 v50, 0xffff0000, v23
	v_fmac_f32_e32 v13, v39, v39
	v_lshlrev_b32_e32 v37, 16, v8
	v_mul_f32_e32 v8, v36, v36
	v_and_b32_e32 v34, 0xffff0000, v9
	v_add_f32_e32 v26, v26, v27
	v_fmac_f32_e32 v22, v53, v53
	v_lshlrev_b32_e32 v51, 16, v23
	v_mul_f32_e32 v23, v50, v50
	v_add_f32_e32 v12, v12, v13
	v_fmac_f32_e32 v8, v37, v37
	v_lshlrev_b32_e32 v35, 16, v9
	v_mul_f32_e32 v9, v34, v34
	v_add_f32_e32 v22, v26, v22
	v_fmac_f32_e32 v23, v51, v51
	v_and_b32_e32 v48, 0xffff0000, v24
	v_add_f32_e32 v8, v12, v8
	v_fmac_f32_e32 v9, v35, v35
	v_and_b32_e32 v32, 0xffff0000, v10
	v_add_f32_e32 v22, v22, v23
	v_lshlrev_b32_e32 v49, 16, v24
	v_mul_f32_e32 v23, v48, v48
	v_add_f32_e32 v8, v8, v9
	v_lshlrev_b32_e32 v33, 16, v10
	v_mul_f32_e32 v9, v32, v32
	v_fmac_f32_e32 v23, v49, v49
	v_and_b32_e32 v44, 0xffff0000, v25
	v_fmac_f32_e32 v9, v33, v33
	v_and_b32_e32 v30, 0xffff0000, v11
	v_add_f32_e32 v22, v22, v23
	v_lshlrev_b32_e32 v45, 16, v25
	v_mul_f32_e32 v23, v44, v44
	v_add_f32_e32 v8, v8, v9
	v_lshlrev_b32_e32 v31, 16, v11
	v_mul_f32_e32 v9, v30, v30
	v_and_b32_e32 v28, 0xffff0000, v4
	v_fmac_f32_e32 v23, v45, v45
	v_fmac_f32_e32 v9, v31, v31
	v_lshlrev_b32_e32 v29, 16, v4
	v_mul_f32_e32 v4, v28, v28
	v_and_b32_e32 v26, 0xffff0000, v5
	v_add_f32_e32 v22, v22, v23
	v_add_f32_e32 v8, v8, v9
	v_fmac_f32_e32 v4, v29, v29
	v_lshlrev_b32_e32 v27, 16, v5
	v_mul_f32_e32 v5, v26, v26
	v_add_f32_dpp v22, v22, v22 quad_perm:[1,0,3,2] row_mask:0xf bank_mask:0xf bound_ctrl:1
	v_add_f32_e32 v4, v8, v4
	v_fmac_f32_e32 v5, v27, v27
	v_and_b32_e32 v24, 0xffff0000, v6
	v_add_f32_dpp v22, v22, v22 quad_perm:[2,3,0,1] row_mask:0xf bank_mask:0xf bound_ctrl:1
	v_add_f32_e32 v4, v4, v5
	v_lshlrev_b32_e32 v25, 16, v6
	v_mul_f32_e32 v5, v24, v24
	v_add_f32_dpp v62, v22, v22 row_half_mirror row_mask:0xf bank_mask:0xf bound_ctrl:1
	v_fmac_f32_e32 v5, v25, v25
	v_and_b32_e32 v22, 0xffff0000, v7
	v_add_f32_e32 v4, v4, v5
	v_lshlrev_b32_e32 v23, 16, v7
	v_mul_f32_e32 v5, v22, v22
	v_and_b32_e32 v14, 0xffff0000, v0
	v_fmac_f32_e32 v5, v23, v23
	v_lshlrev_b32_e32 v15, 16, v0
	v_mul_f32_e32 v0, v14, v14
	v_and_b32_e32 v12, 0xffff0000, v1
	v_add_f32_e32 v4, v4, v5
	v_fmac_f32_e32 v0, v15, v15
	v_lshlrev_b32_e32 v13, 16, v1
	v_mul_f32_e32 v1, v12, v12
	v_add_f32_e32 v0, v4, v0
	v_fmac_f32_e32 v1, v13, v13
	v_and_b32_e32 v10, 0xffff0000, v2
	v_add_f32_e32 v0, v0, v1
	v_lshlrev_b32_e32 v11, 16, v2
	v_mul_f32_e32 v1, v10, v10
	v_fmac_f32_e32 v1, v11, v11
	v_and_b32_e32 v8, 0xffff0000, v3
	v_add_f32_e32 v0, v0, v1
	v_lshlrev_b32_e32 v9, 16, v3
	v_mul_f32_e32 v1, v8, v8
	v_fmac_f32_e32 v1, v9, v9
	v_add_f32_e32 v0, v0, v1
	v_mov_b32_dpp v82, v62 row_mirror row_mask:0xf bank_mask:0xf
	v_lshl_add_u64 v[6:7], v[18:19], 0, s[12:13]
	v_add_f32_dpp v0, v0, v0 quad_perm:[1,0,3,2] row_mask:0xf bank_mask:0xf bound_ctrl:1
	s_nop 1
	v_add_f32_dpp v0, v0, v0 quad_perm:[2,3,0,1] row_mask:0xf bank_mask:0xf bound_ctrl:1
	s_nop 1
	v_add_f32_dpp v54, v0, v0 row_half_mirror row_mask:0xf bank_mask:0xf bound_ctrl:1
	v_add_f32_e32 v0, v62, v82
	v_fmamk_f32 v0, v0, 0x3b000000, v231
	v_cmp_gt_f32_e32 vcc, s18, v0
	v_mul_f32_e32 v1, 0x4f800000, v0
	v_mov_b32_dpp v55, v54 row_mirror row_mask:0xf bank_mask:0xf
	v_cndmask_b32_e32 v0, v0, v1, vcc
	v_sqrt_f32_e32 v1, v0
	s_nop 0
	v_add_u32_e32 v2, -1, v1
	v_fma_f32 v3, -v2, v1, v0
	v_cmp_ge_f32_e64 s[42:43], 0, v3
	v_add_u32_e32 v3, 1, v1
	s_nop 0
	v_cndmask_b32_e64 v2, v1, v2, s[42:43]
	v_fma_f32 v1, -v3, v1, v0
	v_cmp_lt_f32_e64 s[42:43], 0, v1
	s_nop 1
	v_cndmask_b32_e64 v1, v2, v3, s[42:43]
	v_mul_f32_e32 v2, 0x37800000, v1
	v_cndmask_b32_e32 v1, v1, v2, vcc
	v_cmp_class_f32_e32 vcc, v0, v230
	s_nop 1
	v_cndmask_b32_e32 v0, v1, v0, vcc
	v_div_scale_f32 v1, s[18:19], v0, v0, 1.0
	v_rcp_f32_e32 v2, v1
	s_nop 0
	v_fma_f32 v3, -v1, v2, 1.0
	v_fmac_f32_e32 v2, v3, v2
	v_div_scale_f32 v3, vcc, 1.0, v0, 1.0
	v_mul_f32_e32 v4, v3, v2
	v_fma_f32 v5, -v1, v4, v3
	v_fmac_f32_e32 v4, v5, v2
	v_fma_f32 v1, -v1, v4, v3
	v_div_fmas_f32 v1, v1, v2, v4
	v_div_fixup_f32 v62, v1, v0, 1.0
	global_load_dwordx4 v[0:3], v[6:7], off
	global_load_dwordx4 v[84:87], v[6:7], off offset:16
	global_load_dwordx4 v[88:91], v[6:7], off offset:32
	global_load_dwordx4 v[92:95], v[6:7], off offset:48
	v_mul_f32_e32 v79, v62, v79
	v_mul_f32_e32 v77, v62, v77
	v_mul_f32_e32 v75, v62, v75
	v_mul_f32_e32 v73, v62, v73
	v_mul_f32_e32 v80, v62, v80
	v_mul_f32_e32 v78, v62, v78
	v_mul_f32_e32 v76, v62, v76
	v_mul_f32_e32 v74, v62, v74
	v_lshl_add_u64 v[4:5], v[20:21], 0, s[12:13]
	v_mul_f32_e32 v71, v62, v71
	v_mul_f32_e32 v69, v62, v69
	v_mul_f32_e32 v67, v62, v67
	v_mul_f32_e32 v65, v62, v65
	v_mul_f32_e32 v72, v62, v72
	v_mul_f32_e32 v70, v62, v70
	v_mul_f32_e32 v68, v62, v68
	v_mul_f32_e32 v66, v62, v66
	v_mul_f32_e32 v63, v62, v63
	v_mul_f32_e32 v60, v62, v60
	v_mul_f32_e32 v58, v62, v58
	v_mul_f32_e32 v56, v62, v56
	v_mul_f32_e32 v64, v62, v64
	v_mul_f32_e32 v61, v62, v61
	v_mul_f32_e32 v59, v62, v59
	v_mul_f32_e32 v57, v62, v57
	s_waitcnt vmcnt(3)
	v_lshlrev_b32_e32 v82, 16, v0
	v_and_b32_e32 v0, 0xffff0000, v0
	v_mul_f32_e32 v0, v79, v0
	v_lshlrev_b32_e32 v79, 16, v1
	v_and_b32_e32 v1, 0xffff0000, v1
	v_mul_f32_e32 v1, v77, v1
	v_lshlrev_b32_e32 v77, 16, v2
	v_and_b32_e32 v2, 0xffff0000, v2
	v_mul_f32_e32 v2, v75, v2
	v_lshlrev_b32_e32 v75, 16, v3
	v_and_b32_e32 v3, 0xffff0000, v3
	v_mul_f32_e32 v3, v73, v3
	v_mul_f32_e32 v80, v80, v82
	v_cvt_pk_bf16_f32 v0, v80, v0
	v_mul_f32_e32 v78, v78, v79
	v_cvt_pk_bf16_f32 v1, v78, v1
	v_mul_f32_e32 v76, v76, v77
	v_cvt_pk_bf16_f32 v2, v76, v2
	v_mul_f32_e32 v74, v74, v75
	v_cvt_pk_bf16_f32 v3, v74, v3
	global_store_dwordx4 v[4:5], v[0:3], off
	s_waitcnt vmcnt(3)
	s_nop 0
	v_mov_b64_e32 v[0:1], v[84:85]
	v_mov_b64_e32 v[2:3], v[86:87]
	s_nop 0
	v_lshlrev_b32_e32 v73, 16, v0
	v_and_b32_e32 v0, 0xffff0000, v0
	v_mul_f32_e32 v0, v71, v0
	v_lshlrev_b32_e32 v71, 16, v1
	v_and_b32_e32 v1, 0xffff0000, v1
	v_mul_f32_e32 v1, v69, v1
	v_lshlrev_b32_e32 v69, 16, v2
	v_and_b32_e32 v2, 0xffff0000, v2
	v_mul_f32_e32 v2, v67, v2
	v_lshlrev_b32_e32 v67, 16, v3
	v_and_b32_e32 v3, 0xffff0000, v3
	v_mul_f32_e32 v3, v65, v3
	v_mul_f32_e32 v72, v72, v73
	v_cvt_pk_bf16_f32 v0, v72, v0
	v_mul_f32_e32 v70, v70, v71
	v_cvt_pk_bf16_f32 v1, v70, v1
	v_mul_f32_e32 v68, v68, v69
	v_cvt_pk_bf16_f32 v2, v68, v2
	v_mul_f32_e32 v66, v66, v67
	v_cvt_pk_bf16_f32 v3, v66, v3
	global_store_dwordx4 v[4:5], v[0:3], off offset:16
	s_waitcnt vmcnt(3)
	s_nop 0
	v_mov_b64_e32 v[0:1], v[88:89]
	v_mov_b64_e32 v[2:3], v[90:91]
	s_nop 0
	v_lshlrev_b32_e32 v65, 16, v0
	v_and_b32_e32 v0, 0xffff0000, v0
	v_mul_f32_e32 v0, v63, v0
	v_lshlrev_b32_e32 v63, 16, v1
	v_and_b32_e32 v1, 0xffff0000, v1
	v_mul_f32_e32 v1, v60, v1
	v_lshlrev_b32_e32 v60, 16, v2
	v_and_b32_e32 v2, 0xffff0000, v2
	v_mul_f32_e32 v2, v58, v2
	v_lshlrev_b32_e32 v58, 16, v3
	v_and_b32_e32 v3, 0xffff0000, v3
	v_mul_f32_e32 v3, v56, v3
	v_mul_f32_e32 v64, v64, v65
	v_cvt_pk_bf16_f32 v0, v64, v0
	v_mul_f32_e32 v61, v61, v63
	v_cvt_pk_bf16_f32 v1, v61, v1
	v_mul_f32_e32 v59, v59, v60
	v_cvt_pk_bf16_f32 v2, v59, v2
	v_mul_f32_e32 v57, v57, v58
	v_cvt_pk_bf16_f32 v3, v57, v3
	global_store_dwordx4 v[4:5], v[0:3], off offset:32
	s_waitcnt vmcnt(3)
	s_nop 0
	v_mov_b64_e32 v[0:1], v[92:93]
	v_mov_b64_e32 v[2:3], v[94:95]
	v_mul_f32_e32 v7, v62, v53
	s_nop 0
	v_lshlrev_b32_e32 v6, 16, v0
	v_and_b32_e32 v0, 0xffff0000, v0
	v_mul_f32_e32 v6, v7, v6
	v_mul_f32_e32 v7, v62, v52
	v_mul_f32_e32 v0, v7, v0
	v_cvt_pk_bf16_f32 v0, v6, v0
	v_lshlrev_b32_e32 v6, 16, v1
	v_mul_f32_e32 v7, v62, v51
	v_and_b32_e32 v1, 0xffff0000, v1
	v_mul_f32_e32 v6, v7, v6
	v_mul_f32_e32 v7, v62, v50
	v_mul_f32_e32 v1, v7, v1
	v_cvt_pk_bf16_f32 v1, v6, v1
	v_lshlrev_b32_e32 v6, 16, v2
	v_mul_f32_e32 v7, v62, v49
	v_and_b32_e32 v2, 0xffff0000, v2
	v_mul_f32_e32 v6, v7, v6
	v_mul_f32_e32 v7, v62, v48
	v_mul_f32_e32 v2, v7, v2
	v_cvt_pk_bf16_f32 v2, v6, v2
	v_lshlrev_b32_e32 v6, 16, v3
	v_mul_f32_e32 v7, v62, v45
	v_and_b32_e32 v3, 0xffff0000, v3
	v_mul_f32_e32 v6, v7, v6
	v_mul_f32_e32 v7, v62, v44
	v_mul_f32_e32 v3, v7, v3
	v_cvt_pk_bf16_f32 v3, v6, v3
	global_store_dwordx4 v[4:5], v[0:3], off offset:48
	s_cbranch_scc1 .LBB0_2726
	s_nop 0
	v_add_f32_e32 v0, v54, v55
	v_fmamk_f32 v0, v0, 0x3b000000, v231
	s_mov_b32 s12, 0xf800000
	v_cmp_gt_f32_e32 vcc, s12, v0
	v_mul_f32_e32 v1, 0x4f800000, v0
	s_nop 0
	v_cndmask_b32_e32 v0, v0, v1, vcc
	v_sqrt_f32_e32 v1, v0
	s_nop 0
	v_add_u32_e32 v2, -1, v1
	v_fma_f32 v3, -v2, v1, v0
	v_cmp_ge_f32_e64 s[42:43], 0, v3
	v_add_u32_e32 v3, 1, v1
	s_nop 0
	v_cndmask_b32_e64 v2, v1, v2, s[42:43]
	v_fma_f32 v1, -v3, v1, v0
	v_cmp_lt_f32_e64 s[42:43], 0, v1
	s_nop 1
	v_cndmask_b32_e64 v1, v2, v3, s[42:43]
	v_mul_f32_e32 v2, 0x37800000, v1
	v_cndmask_b32_e32 v1, v1, v2, vcc
	v_cmp_class_f32_e32 vcc, v0, v230
	s_nop 1
	v_cndmask_b32_e32 v0, v1, v0, vcc
	v_div_scale_f32 v1, s[12:13], v0, v0, 1.0
	v_rcp_f32_e32 v2, v1
	s_nop 0
	v_fma_f32 v3, -v1, v2, 1.0
	v_fmac_f32_e32 v2, v3, v2
	v_div_scale_f32 v3, vcc, 1.0, v0, 1.0
	v_mul_f32_e32 v4, v3, v2
	v_fma_f32 v5, -v1, v4, v3
	v_fmac_f32_e32 v4, v5, v2
	v_fma_f32 v1, -v1, v4, v3
	v_div_fmas_f32 v1, v1, v2, v4
	v_lshl_add_u64 v[2:3], v[18:19], 0, s[4:5]
	global_load_dwordx4 v[48:51], v[2:3], off
	global_load_dwordx4 v[96:99], v[2:3], off offset:16
	global_load_dwordx4 v[100:103], v[2:3], off offset:32
	global_load_dwordx4 v[104:107], v[2:3], off offset:48
	v_div_fixup_f32 v4, v1, v0, 1.0
	v_mul_f32_e32 v7, v4, v47
	v_lshl_add_u64 v[0:1], v[20:21], 0, s[4:5]
	s_waitcnt vmcnt(3)
	v_lshlrev_b32_e32 v5, 16, v48
	v_and_b32_e32 v6, 0xffff0000, v48
	v_mul_f32_e32 v5, v7, v5
	v_mul_f32_e32 v7, v4, v46
	v_mul_f32_e32 v6, v7, v6
	v_cvt_pk_bf16_f32 v44, v5, v6
	v_lshlrev_b32_e32 v5, 16, v49
	v_mul_f32_e32 v7, v4, v43
	v_and_b32_e32 v6, 0xffff0000, v49
	v_mul_f32_e32 v5, v7, v5
	v_mul_f32_e32 v7, v4, v42
	v_mul_f32_e32 v6, v7, v6
	v_cvt_pk_bf16_f32 v45, v5, v6
	v_lshlrev_b32_e32 v5, 16, v50
	v_mul_f32_e32 v7, v4, v41
	v_and_b32_e32 v6, 0xffff0000, v50
	v_mul_f32_e32 v5, v7, v5
	v_mul_f32_e32 v7, v4, v40
	v_mul_f32_e32 v6, v7, v6
	v_cvt_pk_bf16_f32 v46, v5, v6
	v_lshlrev_b32_e32 v5, 16, v51
	v_mul_f32_e32 v7, v4, v39
	v_and_b32_e32 v6, 0xffff0000, v51
	v_mul_f32_e32 v5, v7, v5
	v_mul_f32_e32 v7, v4, v38
	v_mul_f32_e32 v6, v7, v6
	v_cvt_pk_bf16_f32 v47, v5, v6
	s_waitcnt vmcnt(2)
	s_nop 0
	v_mov_b64_e32 v[38:39], v[96:97]
	v_mov_b64_e32 v[40:41], v[98:99]
	v_mul_f32_e32 v7, v4, v37
	global_store_dwordx4 v[0:1], v[44:47], off
	s_nop 0
	v_lshlrev_b32_e32 v5, 16, v38
	v_and_b32_e32 v6, 0xffff0000, v38
	v_mul_f32_e32 v5, v7, v5
	v_mul_f32_e32 v7, v4, v36
	v_mul_f32_e32 v6, v7, v6
	v_cvt_pk_bf16_f32 v36, v5, v6
	v_lshlrev_b32_e32 v5, 16, v39
	v_mul_f32_e32 v7, v4, v35
	v_and_b32_e32 v6, 0xffff0000, v39
	v_mul_f32_e32 v5, v7, v5
	v_mul_f32_e32 v7, v4, v34
	v_mul_f32_e32 v6, v7, v6
	v_cvt_pk_bf16_f32 v37, v5, v6
	v_lshlrev_b32_e32 v5, 16, v40
	v_mul_f32_e32 v7, v4, v33
	v_and_b32_e32 v6, 0xffff0000, v40
	v_mul_f32_e32 v5, v7, v5
	v_mul_f32_e32 v7, v4, v32
	v_mul_f32_e32 v6, v7, v6
	v_cvt_pk_bf16_f32 v38, v5, v6
	v_lshlrev_b32_e32 v5, 16, v41
	v_mul_f32_e32 v7, v4, v31
	v_and_b32_e32 v6, 0xffff0000, v41
	v_mul_f32_e32 v5, v7, v5
	v_mul_f32_e32 v7, v4, v30
	v_mul_f32_e32 v6, v7, v6
	v_cvt_pk_bf16_f32 v39, v5, v6
	s_waitcnt vmcnt(2)
	s_nop 0
	v_mov_b64_e32 v[30:31], v[100:101]
	v_mov_b64_e32 v[32:33], v[102:103]
	v_mul_f32_e32 v7, v4, v29
	global_store_dwordx4 v[0:1], v[36:39], off offset:16
	s_nop 0
	v_lshlrev_b32_e32 v5, 16, v30
	v_and_b32_e32 v6, 0xffff0000, v30
	v_mul_f32_e32 v5, v7, v5
	v_mul_f32_e32 v7, v4, v28
	v_mul_f32_e32 v6, v7, v6
	v_cvt_pk_bf16_f32 v28, v5, v6
	v_lshlrev_b32_e32 v5, 16, v31
	v_mul_f32_e32 v7, v4, v27
	v_and_b32_e32 v6, 0xffff0000, v31
	v_mul_f32_e32 v5, v7, v5
	v_mul_f32_e32 v7, v4, v26
	v_mul_f32_e32 v6, v7, v6
	v_cvt_pk_bf16_f32 v29, v5, v6
	v_lshlrev_b32_e32 v5, 16, v32
	v_mul_f32_e32 v7, v4, v25
	v_and_b32_e32 v6, 0xffff0000, v32
	v_mul_f32_e32 v5, v7, v5
	v_mul_f32_e32 v7, v4, v24
	v_mul_f32_e32 v6, v7, v6
	v_cvt_pk_bf16_f32 v30, v5, v6
	v_lshlrev_b32_e32 v5, 16, v33
	v_mul_f32_e32 v7, v4, v23
	v_and_b32_e32 v6, 0xffff0000, v33
	v_mul_f32_e32 v5, v7, v5
	v_mul_f32_e32 v7, v4, v22
	v_mul_f32_e32 v6, v7, v6
	v_cvt_pk_bf16_f32 v31, v5, v6
	s_waitcnt vmcnt(2)
	s_nop 0
	v_mov_b64_e32 v[22:23], v[104:105]
	v_mov_b64_e32 v[24:25], v[106:107]
	v_mul_f32_e32 v5, v4, v15
	global_store_dwordx4 v[0:1], v[28:31], off offset:32
	s_nop 0
	v_lshlrev_b32_e32 v2, 16, v22
	v_and_b32_e32 v3, 0xffff0000, v22
	v_mul_f32_e32 v2, v5, v2
	v_mul_f32_e32 v5, v4, v14
	v_mul_f32_e32 v3, v5, v3
	v_cvt_pk_bf16_f32 v22, v2, v3
	v_lshlrev_b32_e32 v2, 16, v23
	v_mul_f32_e32 v5, v4, v13
	v_and_b32_e32 v3, 0xffff0000, v23
	v_mul_f32_e32 v2, v5, v2
	v_mul_f32_e32 v5, v4, v12
	v_mul_f32_e32 v3, v5, v3
	v_cvt_pk_bf16_f32 v23, v2, v3
	v_lshlrev_b32_e32 v2, 16, v24
	v_mul_f32_e32 v5, v4, v11
	v_and_b32_e32 v3, 0xffff0000, v24
	v_mul_f32_e32 v2, v5, v2
	v_mul_f32_e32 v5, v4, v10
	v_mul_f32_e32 v3, v5, v3
	v_cvt_pk_bf16_f32 v24, v2, v3
	v_lshlrev_b32_e32 v2, 16, v25
	v_and_b32_e32 v3, 0xffff0000, v25
	v_mul_f32_e32 v5, v4, v9
	v_mul_f32_e32 v4, v4, v8
	v_mul_f32_e32 v2, v5, v2
	v_mul_f32_e32 v3, v4, v3
	v_cvt_pk_bf16_f32 v25, v2, v3
	global_store_dwordx4 v[0:1], v[22:25], off offset:48
	s_branch .LBB0_2726

.Lslab_skip_a:
	v_and_b32_e32 v1, 64, v235
	v_add_u32_e32 v1, 64, v1
	v_xor_b32_e32 v2, 1, v235
	v_cmp_lt_i32_e32 vcc, v2, v1
	v_and_b32_e32 v0, 63, v0
	v_readlane_b32 s12, v250, 41
	v_cndmask_b32_e32 v2, v235, v2, vcc
	s_waitcnt vmcnt(2)
	v_lshlrev_b32_e32 v60, 2, v2
	v_xor_b32_e32 v2, 2, v235
	v_cmp_lt_i32_e32 vcc, v2, v1
	v_lshlrev_b32_e32 v80, 4, v0
	v_readlane_b32 s13, v250, 42
	v_cndmask_b32_e32 v2, v235, v2, vcc
	v_lshlrev_b32_e32 v61, 2, v2
	v_xor_b32_e32 v2, 4, v235
	v_cmp_lt_i32_e32 vcc, v2, v1
	v_lshl_add_u64 v[36:37], s[12:13], 0, v[80:81]
	v_readlane_b32 s12, v254, 15
	v_cndmask_b32_e32 v2, v235, v2, vcc
	s_waitcnt vmcnt(1)
	v_lshlrev_b32_e32 v62, 2, v2
	v_xor_b32_e32 v2, 8, v235
	v_cmp_lt_i32_e32 vcc, v2, v1
	v_lshlrev_b32_e32 v0, 3, v0
	v_readlane_b32 s13, v254, 16
	v_cndmask_b32_e32 v2, v235, v2, vcc
	v_lshlrev_b32_e32 v63, 2, v2
	v_xor_b32_e32 v2, 16, v235
	v_cmp_lt_i32_e32 vcc, v2, v1
	v_lshl_add_u64 v[38:39], s[4:5], 0, v[80:81]
	s_nop 0
	v_cndmask_b32_e32 v2, v235, v2, vcc
	v_lshlrev_b32_e32 v64, 2, v2
	v_xor_b32_e32 v2, 32, v235
	v_cmp_lt_i32_e32 vcc, v2, v1
	s_nop 1
	v_cndmask_b32_e32 v1, v235, v2, vcc
	v_lshlrev_b32_e32 v65, 2, v1
	v_mov_b32_e32 v1, v81
	v_lshl_add_u64 v[40:41], s[12:13], 0, v[0:1]
	v_readlane_b32 s12, v254, 40
	v_readlane_b32 s13, v254, 41
	s_nop 1
	v_lshl_add_u64 v[42:43], s[12:13], 0, v[80:81]
	v_readlane_b32 s12, v254, 27
	v_readlane_b32 s13, v254, 28
	s_nop 1
	v_lshl_add_u64 v[44:45], s[12:13], 0, v[0:1]
	v_readlane_b32 s12, v250, 6
	s_mov_b32 s7, s12
	v_readlane_b32 s13, v250, 7
	global_load_dwordx4 v[84:87], v[38:39], off
	global_load_dwordx4 v[88:91], v[38:39], off offset:1024
	global_load_dwordx4 v[92:95], v[38:39], off offset:2048
	global_load_dwordx4 v[96:99], v[38:39], off offset:3072
	s_waitcnt vmcnt(0)
	s_branch .LBB0_3021

.LBB0_3021:
	v_readlane_b32 s12, v255, 20
	s_add_i32 s14, s12, s7
	s_cmpk_lt_i32 s14, 0x4100
	v_readlane_b32 s13, v255, 21
	s_cselect_b32 s12, s14, s7
	s_ashr_i32 s13, s12, 31
	v_lshl_add_u64 v[0:1], s[78:79], 0, v[42:43]
	s_lshl_b64 s[12:13], s[12:13], 12
	v_add_co_u32_e32 v14, vcc, 0x7506000, v0
	v_lshl_add_u64 v[12:13], v[36:37], 0, s[12:13]
	s_nop 0
	v_addc_co_u32_e32 v15, vcc, 0, v1, vcc
	global_load_dwordx4 v[20:23], v[14:15], off
	global_load_dwordx4 v[0:3], v[12:13], off
	global_load_dwordx4 v[24:27], v[14:15], off offset:1024
	global_load_dwordx4 v[4:7], v[12:13], off offset:1024
	global_load_dwordx4 v[28:31], v[14:15], off offset:2048
	global_load_dwordx4 v[8:11], v[12:13], off offset:2048
	global_load_dwordx4 v[32:35], v[14:15], off offset:3072
	s_nop 0
	global_load_dwordx4 v[12:15], v[12:13], off offset:3072
	s_mov_b32 s12, 0xf800000
	s_cmpk_gt_i32 s14, 0x40ff
	s_waitcnt vmcnt(7)
	v_pk_mul_f32 v[16:17], v[22:23], v[22:23]
	v_pk_mul_f32 v[18:19], v[20:21], v[20:21]
	s_nop 0
	v_pk_mov_b32 v[46:47], v[18:19], v[16:17] op_sel:[1,0]
	v_mov_b32_e32 v19, v17
	v_pk_add_f32 v[16:17], v[46:47], v[18:19]
	s_waitcnt vmcnt(6)
	v_mul_f32_e32 v18, v1, v1
	v_mul_f32_e32 v19, v3, v3
	v_fmac_f32_e32 v18, v0, v0
	v_fmac_f32_e32 v19, v2, v2
	v_add_f32_e32 v50, v18, v19
	s_waitcnt vmcnt(5)
	v_pk_mul_f32 v[18:19], v[26:27], v[26:27]
	v_pk_mul_f32 v[46:47], v[24:25], v[24:25]
	v_pk_add_f32 v[16:17], v[16:17], v[16:17] op_sel:[0,1] op_sel_hi:[1,0]
	v_pk_mov_b32 v[48:49], v[46:47], v[18:19] op_sel:[1,0]
	v_mov_b32_e32 v47, v19
	v_pk_add_f32 v[18:19], v[48:49], v[46:47]
	s_waitcnt vmcnt(4)
	v_mul_f32_e32 v46, v5, v5
	v_mul_f32_e32 v47, v7, v7
	v_fmac_f32_e32 v46, v4, v4
	v_fmac_f32_e32 v47, v6, v6
	v_add_f32_e32 v46, v46, v47
	s_waitcnt vmcnt(2)
	v_mul_f32_e32 v47, v9, v9
	v_mul_f32_e32 v48, v11, v11
	v_fmac_f32_e32 v47, v8, v8
	v_fmac_f32_e32 v48, v10, v10
	v_add_f32_e32 v46, v50, v46
	v_add_f32_e32 v47, v47, v48
	v_add_f32_e32 v48, v46, v47
	s_waitcnt vmcnt(1)
	v_mul_f32_e32 v46, v32, v32
	v_mul_f32_e32 v47, v33, v33
	v_pk_add_f32 v[18:19], v[18:19], v[18:19] op_sel:[0,1] op_sel_hi:[1,0]
	v_mov_b32_e32 v17, v46
	v_mov_b32_e32 v19, v47
	v_pk_add_f32 v[16:17], v[16:17], v[18:19]
	v_mul_f32_e32 v18, v29, v29
	v_mul_f32_e32 v46, v31, v31
	v_mul_f32_e32 v49, v34, v34
	v_mul_f32_e32 v50, v35, v35
	v_pk_fma_f32 v[18:19], v[28:29], v[28:29], v[18:19] op_sel_hi:[1,1,0]
	v_pk_fma_f32 v[46:47], v[30:31], v[30:31], v[46:47] op_sel_hi:[1,1,0]
	v_mov_b32_e32 v19, v49
	v_mov_b32_e32 v47, v50
	v_pk_add_f32 v[18:19], v[18:19], v[46:47]
	s_nop 0
	v_pk_add_f32 v[16:17], v[16:17], v[18:19]
	s_waitcnt vmcnt(0)
	v_mul_f32_e32 v18, v15, v15
	v_add_f32_e32 v16, v16, v17
	v_mul_f32_e32 v17, v13, v13
	v_fmac_f32_e32 v17, v12, v12
	v_fmac_f32_e32 v18, v14, v14
	v_add_f32_e32 v17, v17, v18
	ds_bpermute_b32 v18, v60, v16
	v_add_f32_e32 v17, v48, v17
	s_waitcnt lgkmcnt(0)
	v_add_f32_e32 v16, v16, v18
	ds_bpermute_b32 v18, v60, v17
	s_waitcnt lgkmcnt(0)
	v_add_f32_e32 v17, v17, v18
	ds_bpermute_b32 v18, v61, v16
	s_waitcnt lgkmcnt(0)
	v_add_f32_e32 v16, v16, v18
	ds_bpermute_b32 v18, v61, v17
	s_waitcnt lgkmcnt(0)
	v_add_f32_e32 v17, v17, v18
	ds_bpermute_b32 v18, v62, v16
	s_waitcnt lgkmcnt(0)
	v_add_f32_e32 v16, v16, v18
	ds_bpermute_b32 v18, v62, v17
	s_waitcnt lgkmcnt(0)
	v_add_f32_e32 v17, v17, v18
	ds_bpermute_b32 v18, v63, v16
	s_waitcnt lgkmcnt(0)
	v_add_f32_e32 v16, v16, v18
	ds_bpermute_b32 v18, v63, v17
	s_waitcnt lgkmcnt(0)
	v_add_f32_e32 v17, v17, v18
	ds_bpermute_b32 v18, v64, v16
	s_waitcnt lgkmcnt(0)
	v_add_f32_e32 v16, v16, v18
	ds_bpermute_b32 v18, v64, v17
	s_waitcnt lgkmcnt(0)
	v_add_f32_e32 v66, v17, v18
	ds_bpermute_b32 v17, v65, v16
	ds_bpermute_b32 v67, v65, v66
	s_waitcnt lgkmcnt(1)
	v_add_f32_e32 v16, v16, v17
	v_fmamk_f32 v16, v16, 0x3a800000, v231
	v_cmp_gt_f32_e32 vcc, s12, v16
	v_mul_f32_e32 v17, 0x4f800000, v16
	s_nop 0
	v_cndmask_b32_e32 v16, v16, v17, vcc
	v_sqrt_f32_e32 v17, v16
	s_nop 0
	v_add_u32_e32 v18, -1, v17
	v_fma_f32 v19, -v18, v17, v16
	v_cmp_ge_f32_e64 s[46:47], 0, v19
	v_add_u32_e32 v19, 1, v17
	s_nop 0
	v_cndmask_b32_e64 v18, v17, v18, s[46:47]
	v_fma_f32 v17, -v19, v17, v16
	v_cmp_lt_f32_e64 s[46:47], 0, v17
	s_nop 1
	v_cndmask_b32_e64 v17, v18, v19, s[46:47]
	v_mul_f32_e32 v18, 0x37800000, v17
	v_cndmask_b32_e32 v17, v17, v18, vcc
	v_cmp_class_f32_e32 vcc, v16, v230
	s_nop 1
	v_cndmask_b32_e32 v16, v17, v16, vcc
	v_div_scale_f32 v17, s[12:13], v16, v16, 1.0
	v_rcp_f32_e32 v18, v17
	s_nop 0
	v_fma_f32 v19, -v17, v18, 1.0
	v_fmac_f32_e32 v18, v19, v18
	v_div_scale_f32 v19, vcc, 1.0, v16, 1.0
	v_mul_f32_e32 v46, v19, v18
	v_fma_f32 v47, -v17, v46, v19
	v_fmac_f32_e32 v46, v47, v18
	v_fma_f32 v17, -v17, v46, v19
	v_div_fmas_f32 v17, v17, v18, v46
	v_div_fixup_f32 v54, v17, v16, 1.0
	v_mov_b64_e32 v[16:17], v[84:85]
	v_mov_b64_e32 v[18:19], v[86:87]
	v_pk_mul_f32 v[20:21], v[20:21], v[54:55] op_sel_hi:[1,0]
	v_pk_mul_f32 v[22:23], v[22:23], v[54:55] op_sel_hi:[1,0]
	v_pk_mul_f32 v[24:25], v[24:25], v[54:55] op_sel_hi:[1,0]
	v_pk_mul_f32 v[26:27], v[26:27], v[54:55] op_sel_hi:[1,0]
	v_pk_mul_f32 v[28:29], v[28:29], v[54:55] op_sel_hi:[1,0]
	v_pk_mul_f32 v[30:31], v[30:31], v[54:55] op_sel_hi:[1,0]
	v_pk_mul_f32 v[68:69], v[32:33], v[54:55] op_sel_hi:[1,0]
	v_pk_mul_f32 v[32:33], v[34:35], v[54:55] op_sel_hi:[1,0]
	v_lshl_add_u64 v[54:55], s[78:79], 0, v[40:41]
	v_add_co_u32_e32 v54, vcc, s26, v54
	s_nop 0
	v_pk_mul_f32 v[56:57], v[18:19], v[22:23]
	v_pk_mul_f32 v[58:59], v[16:17], v[20:21]
	v_mov_b64_e32 v[20:21], v[88:89]
	v_mov_b64_e32 v[22:23], v[90:91]
	v_addc_co_u32_e32 v55, vcc, 0, v55, vcc
	s_nop 0
	v_pk_mul_f32 v[46:47], v[22:23], v[26:27]
	v_pk_mul_f32 v[48:49], v[20:21], v[24:25]
	v_mov_b64_e32 v[24:25], v[92:93]
	v_mov_b64_e32 v[26:27], v[94:95]
	s_nop 0
	v_pk_mul_f32 v[50:51], v[26:27], v[30:31]
	v_pk_mul_f32 v[52:53], v[24:25], v[28:29]
	v_mov_b64_e32 v[28:29], v[96:97]
	v_mov_b64_e32 v[30:31], v[98:99]
	s_nop 0
	v_pk_mul_f32 v[34:35], v[28:29], v[68:69]
	v_bfe_u32 v68, v58, 16, 1
	v_add3_u32 v58, v58, v68, s89
	v_bfe_u32 v68, v59, 16, 1
	v_lshrrev_b32_e32 v58, 16, v58
	v_add3_u32 v59, v59, v68, s89
	v_and_or_b32 v58, v59, s31, v58
	v_bfe_u32 v59, v56, 16, 1
	v_add3_u32 v56, v56, v59, s89
	v_bfe_u32 v59, v57, 16, 1
	v_lshrrev_b32_e32 v56, 16, v56
	v_add3_u32 v57, v57, v59, s89
	v_and_or_b32 v59, v57, s31, v56
	v_bfe_u32 v56, v48, 16, 1
	v_add3_u32 v48, v48, v56, s89
	v_bfe_u32 v56, v49, 16, 1
	v_lshrrev_b32_e32 v48, 16, v48
	v_add3_u32 v49, v49, v56, s89
	v_and_or_b32 v48, v49, s31, v48
	v_bfe_u32 v49, v46, 16, 1
	v_add3_u32 v46, v46, v49, s89
	v_bfe_u32 v49, v47, 16, 1
	v_lshrrev_b32_e32 v46, 16, v46
	v_add3_u32 v47, v47, v49, s89
	v_and_or_b32 v49, v47, s31, v46
	v_bfe_u32 v46, v52, 16, 1
	v_add3_u32 v46, v52, v46, s89
	v_bfe_u32 v47, v53, 16, 1
	v_lshrrev_b32_e32 v46, 16, v46
	v_add3_u32 v47, v53, v47, s89
	v_and_or_b32 v46, v47, s31, v46
	v_bfe_u32 v47, v50, 16, 1
	global_store_dwordx2 v[54:55], v[48:49], off offset:512
	v_add3_u32 v47, v50, v47, s89
	v_bfe_u32 v48, v51, 16, 1
	v_lshrrev_b32_e32 v47, 16, v47
	v_add3_u32 v48, v51, v48, s89
	v_and_or_b32 v47, v48, s31, v47
	global_store_dwordx2 v[54:55], v[46:47], off offset:1024
	v_bfe_u32 v46, v34, 16, 1
	v_add3_u32 v34, v34, v46, s89
	v_bfe_u32 v46, v35, 16, 1
	v_pk_mul_f32 v[32:33], v[30:31], v[32:33]
	v_lshrrev_b32_e32 v34, 16, v34
	v_add3_u32 v35, v35, v46, s89
	v_and_or_b32 v34, v35, s31, v34
	v_bfe_u32 v35, v32, 16, 1
	v_add3_u32 v32, v32, v35, s89
	v_bfe_u32 v35, v33, 16, 1
	v_lshrrev_b32_e32 v32, 16, v32
	v_add3_u32 v33, v33, v35, s89
	v_and_or_b32 v35, v33, s31, v32
	global_store_dwordx2 v[54:55], v[58:59], off
	global_store_dwordx2 v[54:55], v[34:35], off offset:1536
	s_cbranch_scc1 .LBB0_3020
	s_waitcnt lgkmcnt(0)
	v_add_f32_e32 v32, v66, v67
	v_fmamk_f32 v32, v32, 0x3a800000, v231
	s_mov_b32 s12, 0xf800000
	v_mul_f32_e32 v33, 0x4f800000, v32
	v_cmp_gt_f32_e32 vcc, s12, v32
	s_nop 1
	v_cndmask_b32_e32 v32, v32, v33, vcc
	v_sqrt_f32_e32 v33, v32
	s_nop 0
	v_add_u32_e32 v34, -1, v33
	v_fma_f32 v46, -v34, v33, v32
	v_add_u32_e32 v35, 1, v33
	v_cmp_ge_f32_e64 s[46:47], 0, v46
	s_nop 1
	v_cndmask_b32_e64 v34, v33, v34, s[46:47]
	v_fma_f32 v33, -v35, v33, v32
	v_cmp_lt_f32_e64 s[46:47], 0, v33
	s_nop 1
	v_cndmask_b32_e64 v33, v34, v35, s[46:47]
	v_mul_f32_e32 v34, 0x37800000, v33
	v_cndmask_b32_e32 v33, v33, v34, vcc
	v_cmp_class_f32_e32 vcc, v32, v230
	s_nop 1
	v_cndmask_b32_e32 v32, v33, v32, vcc
	v_div_scale_f32 v33, s[12:13], v32, v32, 1.0
	v_rcp_f32_e32 v34, v33
	s_nop 0
	v_fma_f32 v35, -v33, v34, 1.0
	v_fmac_f32_e32 v34, v35, v34
	v_div_scale_f32 v35, vcc, 1.0, v32, 1.0
	v_mul_f32_e32 v46, v35, v34
	v_fma_f32 v47, -v33, v46, v35
	v_fmac_f32_e32 v46, v47, v34
	v_fma_f32 v33, -v33, v46, v35
	v_div_fmas_f32 v33, v33, v34, v46
	v_div_fixup_f32 v32, v33, v32, 1.0
	v_pk_mul_f32 v[0:1], v[0:1], v[32:33] op_sel_hi:[1,0]
	v_pk_mul_f32 v[2:3], v[2:3], v[32:33] op_sel_hi:[1,0]
	v_pk_mul_f32 v[0:1], v[16:17], v[0:1]
	v_pk_mul_f32 v[2:3], v[18:19], v[2:3]
	v_bfe_u32 v18, v0, 16, 1
	v_add3_u32 v0, v0, v18, s89
	v_bfe_u32 v18, v1, 16, 1
	v_lshrrev_b32_e32 v0, 16, v0
	v_add3_u32 v1, v1, v18, s89
	v_and_or_b32 v0, v1, s31, v0
	v_bfe_u32 v1, v2, 16, 1
	v_add3_u32 v1, v2, v1, s89
	v_bfe_u32 v2, v3, 16, 1
	v_lshl_add_u64 v[16:17], s[78:79], 0, v[44:45]
	v_lshrrev_b32_e32 v1, 16, v1
	v_add3_u32 v2, v3, v2, s89
	v_pk_mul_f32 v[4:5], v[4:5], v[32:33] op_sel_hi:[1,0]
	v_and_or_b32 v1, v2, s31, v1
	v_add_co_u32_e32 v2, vcc, s26, v16
	v_pk_mul_f32 v[4:5], v[20:21], v[4:5]
	s_nop 0
	v_addc_co_u32_e32 v3, vcc, 0, v17, vcc
	global_store_dwordx2 v[2:3], v[0:1], off
	v_bfe_u32 v0, v4, 16, 1
	v_pk_mul_f32 v[6:7], v[6:7], v[32:33] op_sel_hi:[1,0]
	v_add3_u32 v0, v4, v0, s89
	v_bfe_u32 v1, v5, 16, 1
	v_pk_mul_f32 v[6:7], v[22:23], v[6:7]
	v_lshrrev_b32_e32 v0, 16, v0
	v_add3_u32 v1, v5, v1, s89
	v_and_or_b32 v0, v1, s31, v0
	v_bfe_u32 v1, v6, 16, 1
	v_add3_u32 v1, v6, v1, s89
	v_bfe_u32 v4, v7, 16, 1
	v_pk_mul_f32 v[8:9], v[8:9], v[32:33] op_sel_hi:[1,0]
	v_lshrrev_b32_e32 v1, 16, v1
	v_add3_u32 v4, v7, v4, s89
	v_pk_mul_f32 v[8:9], v[24:25], v[8:9]
	v_and_or_b32 v1, v4, s31, v1
	global_store_dwordx2 v[2:3], v[0:1], off offset:512
	v_bfe_u32 v0, v8, 16, 1
	v_pk_mul_f32 v[10:11], v[10:11], v[32:33] op_sel_hi:[1,0]
	v_add3_u32 v0, v8, v0, s89
	v_bfe_u32 v1, v9, 16, 1
	v_pk_mul_f32 v[10:11], v[26:27], v[10:11]
	v_lshrrev_b32_e32 v0, 16, v0
	v_add3_u32 v1, v9, v1, s89
	v_and_or_b32 v0, v1, s31, v0
	v_bfe_u32 v1, v10, 16, 1
	v_add3_u32 v1, v10, v1, s89
	v_bfe_u32 v4, v11, 16, 1
	v_pk_mul_f32 v[12:13], v[12:13], v[32:33] op_sel_hi:[1,0]
	v_lshrrev_b32_e32 v1, 16, v1
	v_add3_u32 v4, v11, v4, s89
	v_pk_mul_f32 v[12:13], v[28:29], v[12:13]
	v_and_or_b32 v1, v4, s31, v1
	global_store_dwordx2 v[2:3], v[0:1], off offset:1024
	v_bfe_u32 v0, v12, 16, 1
	v_pk_mul_f32 v[14:15], v[14:15], v[32:33] op_sel_hi:[1,0]
	v_add3_u32 v0, v12, v0, s89
	v_bfe_u32 v1, v13, 16, 1
	v_pk_mul_f32 v[14:15], v[30:31], v[14:15]
	v_lshrrev_b32_e32 v0, 16, v0
	v_add3_u32 v1, v13, v1, s89
	v_and_or_b32 v0, v1, s31, v0
	v_bfe_u32 v1, v14, 16, 1
	v_add3_u32 v1, v14, v1, s89
	v_bfe_u32 v4, v15, 16, 1
	v_lshrrev_b32_e32 v1, 16, v1
	v_add3_u32 v4, v15, v4, s89
	v_and_or_b32 v1, v4, s31, v1
	global_store_dwordx2 v[2:3], v[0:1], off offset:1536
	s_branch .LBB0_3020

.Lslab_skip_b:
	v_readlane_b32 s26, v255, 40
	v_mov_b32_e32 v0, v226
	v_readlane_b32 s27, v255, 41
	s_mov_b64 s[18:19], -1
	v_and_b32_e32 v148, 63, v0
	s_and_b64 vcc, exec, s[26:27]
	v_readlane_b32 s46, v253, 9
	v_readlane_b32 s47, v253, 10
	s_cbranch_vccz .LBB0_3475
	s_and_b64 vcc, exec, s[4:5]
	s_cbranch_vccz .LBB0_3460
	v_readlane_b32 s18, v252, 30
	v_readlane_b32 s19, v252, 31
	s_andn2_b64 vcc, exec, s[18:19]
	s_cbranch_vccnz .LBB0_3459
	v_and_b32_e32 v0, 64, v235
	v_add_u32_e32 v0, 64, v0
	v_xor_b32_e32 v1, 1, v235
	v_cmp_lt_i32_e32 vcc, v1, v0
	v_readlane_b32 s18, v250, 41
	v_lshlrev_b32_e32 v80, 4, v148
	v_cndmask_b32_e32 v1, v235, v1, vcc
	s_waitcnt vmcnt(2)
	v_lshlrev_b32_e32 v60, 2, v1
	v_xor_b32_e32 v1, 2, v235
	v_cmp_lt_i32_e32 vcc, v1, v0
	v_readlane_b32 s19, v250, 42
	v_lshl_add_u64 v[38:39], s[12:13], 0, v[80:81]
	v_cndmask_b32_e32 v1, v235, v1, vcc
	v_lshlrev_b32_e32 v61, 2, v1
	v_xor_b32_e32 v1, 4, v235
	v_cmp_lt_i32_e32 vcc, v1, v0
	v_lshl_add_u64 v[36:37], s[18:19], 0, v[80:81]
	v_readlane_b32 s18, v254, 15
	v_cndmask_b32_e32 v1, v235, v1, vcc
	s_waitcnt vmcnt(1)
	v_lshlrev_b32_e32 v62, 2, v1
	v_xor_b32_e32 v1, 8, v235
	v_cmp_lt_i32_e32 vcc, v1, v0
	v_readlane_b32 s19, v254, 16
	s_nop 0
	v_cndmask_b32_e32 v1, v235, v1, vcc
	v_lshlrev_b32_e32 v63, 2, v1
	v_xor_b32_e32 v1, 16, v235
	v_cmp_lt_i32_e32 vcc, v1, v0
	s_nop 1
	v_cndmask_b32_e32 v1, v235, v1, vcc
	v_lshlrev_b32_e32 v64, 2, v1
	v_xor_b32_e32 v1, 32, v235
	v_cmp_lt_i32_e32 vcc, v1, v0
	s_nop 1
	v_cndmask_b32_e32 v0, v235, v1, vcc
	v_lshlrev_b32_e32 v65, 2, v0
	v_lshlrev_b32_e32 v0, 3, v148
	v_mov_b32_e32 v1, v81
	v_lshl_add_u64 v[40:41], s[18:19], 0, v[0:1]
	v_readlane_b32 s18, v254, 40
	v_readlane_b32 s19, v254, 41
	s_nop 1
	v_lshl_add_u64 v[42:43], s[18:19], 0, v[80:81]
	v_readlane_b32 s18, v254, 27
	v_readlane_b32 s19, v254, 28
	s_nop 1
	v_lshl_add_u64 v[44:45], s[18:19], 0, v[0:1]
	v_readlane_b32 s18, v250, 6
	s_mov_b32 s7, s18
	v_readlane_b32 s19, v250, 7
	global_load_dwordx4 v[84:87], v[38:39], off
	global_load_dwordx4 v[88:91], v[38:39], off offset:1024
	global_load_dwordx4 v[92:95], v[38:39], off offset:2048
	global_load_dwordx4 v[96:99], v[38:39], off offset:3072
	s_waitcnt vmcnt(0)
	s_branch .LBB0_3457

.LBB0_3457:
	v_readlane_b32 s18, v255, 20
	s_add_i32 s14, s18, s7
	s_cmpk_lt_i32 s14, 0x4100
	v_readlane_b32 s19, v255, 21
	s_cselect_b32 s18, s14, s7
	s_ashr_i32 s19, s18, 31
	v_lshl_add_u64 v[0:1], s[78:79], 0, v[42:43]
	s_lshl_b64 s[18:19], s[18:19], 12
	v_add_co_u32_e32 v14, vcc, 0x7506000, v0
	v_lshl_add_u64 v[12:13], v[36:37], 0, s[18:19]
	s_nop 0
	v_addc_co_u32_e32 v15, vcc, 0, v1, vcc
	global_load_dwordx4 v[20:23], v[14:15], off
	global_load_dwordx4 v[0:3], v[12:13], off
	global_load_dwordx4 v[24:27], v[14:15], off offset:1024
	global_load_dwordx4 v[4:7], v[12:13], off offset:1024
	global_load_dwordx4 v[28:31], v[14:15], off offset:2048
	global_load_dwordx4 v[8:11], v[12:13], off offset:2048
	global_load_dwordx4 v[32:35], v[14:15], off offset:3072
	s_nop 0
	global_load_dwordx4 v[12:15], v[12:13], off offset:3072
	s_cmpk_gt_i32 s14, 0x40ff
	s_mov_b32 s14, 0xb606000
	s_waitcnt vmcnt(7)
	v_pk_mul_f32 v[16:17], v[22:23], v[22:23]
	v_pk_mul_f32 v[18:19], v[20:21], v[20:21]
	s_nop 0
	v_pk_mov_b32 v[46:47], v[18:19], v[16:17] op_sel:[1,0]
	v_mov_b32_e32 v19, v17
	v_pk_add_f32 v[16:17], v[46:47], v[18:19]
	s_waitcnt vmcnt(6)
	v_mul_f32_e32 v18, v1, v1
	v_mul_f32_e32 v19, v3, v3
	v_fmac_f32_e32 v18, v0, v0
	v_fmac_f32_e32 v19, v2, v2
	v_add_f32_e32 v50, v18, v19
	s_waitcnt vmcnt(5)
	v_pk_mul_f32 v[18:19], v[26:27], v[26:27]
	v_pk_mul_f32 v[46:47], v[24:25], v[24:25]
	v_pk_add_f32 v[16:17], v[16:17], v[16:17] op_sel:[0,1] op_sel_hi:[1,0]
	v_pk_mov_b32 v[48:49], v[46:47], v[18:19] op_sel:[1,0]
	v_mov_b32_e32 v47, v19
	v_pk_add_f32 v[18:19], v[48:49], v[46:47]
	s_waitcnt vmcnt(4)
	v_mul_f32_e32 v46, v5, v5
	v_mul_f32_e32 v47, v7, v7
	v_fmac_f32_e32 v46, v4, v4
	v_fmac_f32_e32 v47, v6, v6
	v_add_f32_e32 v46, v46, v47
	s_waitcnt vmcnt(2)
	v_mul_f32_e32 v47, v9, v9
	v_mul_f32_e32 v48, v11, v11
	v_fmac_f32_e32 v47, v8, v8
	v_fmac_f32_e32 v48, v10, v10
	v_add_f32_e32 v46, v50, v46
	v_add_f32_e32 v47, v47, v48
	v_add_f32_e32 v48, v46, v47
	s_waitcnt vmcnt(1)
	v_mul_f32_e32 v46, v32, v32
	v_mul_f32_e32 v47, v33, v33
	v_pk_add_f32 v[18:19], v[18:19], v[18:19] op_sel:[0,1] op_sel_hi:[1,0]
	v_mov_b32_e32 v17, v46
	v_mov_b32_e32 v19, v47
	v_pk_add_f32 v[16:17], v[16:17], v[18:19]
	v_mul_f32_e32 v18, v29, v29
	v_mul_f32_e32 v46, v31, v31
	v_mul_f32_e32 v49, v34, v34
	v_mul_f32_e32 v50, v35, v35
	v_pk_fma_f32 v[18:19], v[28:29], v[28:29], v[18:19] op_sel_hi:[1,1,0]
	v_pk_fma_f32 v[46:47], v[30:31], v[30:31], v[46:47] op_sel_hi:[1,1,0]
	v_mov_b32_e32 v19, v49
	v_mov_b32_e32 v47, v50
	v_pk_add_f32 v[18:19], v[18:19], v[46:47]
	s_nop 0
	v_pk_add_f32 v[16:17], v[16:17], v[18:19]
	s_waitcnt vmcnt(0)
	v_mul_f32_e32 v18, v15, v15
	v_add_f32_e32 v16, v16, v17
	v_mul_f32_e32 v17, v13, v13
	v_fmac_f32_e32 v17, v12, v12
	v_fmac_f32_e32 v18, v14, v14
	v_add_f32_e32 v17, v17, v18
	ds_bpermute_b32 v18, v60, v16
	v_add_f32_e32 v17, v48, v17
	s_waitcnt lgkmcnt(0)
	v_add_f32_e32 v16, v16, v18
	ds_bpermute_b32 v18, v60, v17
	s_waitcnt lgkmcnt(0)
	v_add_f32_e32 v17, v17, v18
	ds_bpermute_b32 v18, v61, v16
	s_waitcnt lgkmcnt(0)
	v_add_f32_e32 v16, v16, v18
	ds_bpermute_b32 v18, v61, v17
	s_waitcnt lgkmcnt(0)
	v_add_f32_e32 v17, v17, v18
	ds_bpermute_b32 v18, v62, v16
	s_waitcnt lgkmcnt(0)
	v_add_f32_e32 v16, v16, v18
	ds_bpermute_b32 v18, v62, v17
	s_waitcnt lgkmcnt(0)
	v_add_f32_e32 v17, v17, v18
	ds_bpermute_b32 v18, v63, v16
	s_waitcnt lgkmcnt(0)
	v_add_f32_e32 v16, v16, v18
	ds_bpermute_b32 v18, v63, v17
	s_waitcnt lgkmcnt(0)
	v_add_f32_e32 v17, v17, v18
	ds_bpermute_b32 v18, v64, v16
	s_waitcnt lgkmcnt(0)
	v_add_f32_e32 v16, v16, v18
	ds_bpermute_b32 v18, v64, v17
	s_waitcnt lgkmcnt(0)
	v_add_f32_e32 v66, v17, v18
	ds_bpermute_b32 v17, v65, v16
	ds_bpermute_b32 v67, v65, v66
	s_waitcnt lgkmcnt(1)
	v_add_f32_e32 v16, v16, v17
	v_fmamk_f32 v16, v16, 0x3a800000, v231
	v_cmp_gt_f32_e32 vcc, s48, v16
	v_mul_f32_e32 v17, 0x4f800000, v16
	s_nop 0
	v_cndmask_b32_e32 v16, v16, v17, vcc
	v_sqrt_f32_e32 v17, v16
	s_nop 0
	v_add_u32_e32 v18, -1, v17
	v_fma_f32 v19, -v18, v17, v16
	v_cmp_ge_f32_e64 s[42:43], 0, v19
	v_add_u32_e32 v19, 1, v17
	s_nop 0
	v_cndmask_b32_e64 v18, v17, v18, s[42:43]
	v_fma_f32 v17, -v19, v17, v16
	v_cmp_lt_f32_e64 s[42:43], 0, v17
	s_nop 1
	v_cndmask_b32_e64 v17, v18, v19, s[42:43]
	v_mul_f32_e32 v18, 0x37800000, v17
	v_cndmask_b32_e32 v17, v17, v18, vcc
	v_cmp_class_f32_e32 vcc, v16, v230
	s_nop 1
	v_cndmask_b32_e32 v16, v17, v16, vcc
	v_div_scale_f32 v17, s[18:19], v16, v16, 1.0
	v_rcp_f32_e32 v18, v17
	s_nop 0
	v_fma_f32 v19, -v17, v18, 1.0
	v_fmac_f32_e32 v18, v19, v18
	v_div_scale_f32 v19, vcc, 1.0, v16, 1.0
	v_mul_f32_e32 v46, v19, v18
	v_fma_f32 v47, -v17, v46, v19
	v_fmac_f32_e32 v46, v47, v18
	v_fma_f32 v17, -v17, v46, v19
	v_div_fmas_f32 v17, v17, v18, v46
	v_div_fixup_f32 v54, v17, v16, 1.0
	v_mov_b64_e32 v[16:17], v[84:85]
	v_mov_b64_e32 v[18:19], v[86:87]
	v_pk_mul_f32 v[20:21], v[20:21], v[54:55] op_sel_hi:[1,0]
	v_pk_mul_f32 v[22:23], v[22:23], v[54:55] op_sel_hi:[1,0]
	v_pk_mul_f32 v[24:25], v[24:25], v[54:55] op_sel_hi:[1,0]
	v_pk_mul_f32 v[26:27], v[26:27], v[54:55] op_sel_hi:[1,0]
	v_pk_mul_f32 v[28:29], v[28:29], v[54:55] op_sel_hi:[1,0]
	v_pk_mul_f32 v[30:31], v[30:31], v[54:55] op_sel_hi:[1,0]
	v_pk_mul_f32 v[68:69], v[32:33], v[54:55] op_sel_hi:[1,0]
	v_pk_mul_f32 v[32:33], v[34:35], v[54:55] op_sel_hi:[1,0]
	v_lshl_add_u64 v[54:55], s[78:79], 0, v[40:41]
	v_add_co_u32_e32 v54, vcc, s14, v54
	s_nop 0
	v_pk_mul_f32 v[56:57], v[18:19], v[22:23]
	v_pk_mul_f32 v[58:59], v[16:17], v[20:21]
	v_mov_b64_e32 v[20:21], v[88:89]
	v_mov_b64_e32 v[22:23], v[90:91]
	v_addc_co_u32_e32 v55, vcc, 0, v55, vcc
	s_nop 0
	v_pk_mul_f32 v[46:47], v[22:23], v[26:27]
	v_pk_mul_f32 v[48:49], v[20:21], v[24:25]
	v_mov_b64_e32 v[24:25], v[92:93]
	v_mov_b64_e32 v[26:27], v[94:95]
	s_nop 0
	v_pk_mul_f32 v[50:51], v[26:27], v[30:31]
	v_pk_mul_f32 v[52:53], v[24:25], v[28:29]
	v_mov_b64_e32 v[28:29], v[96:97]
	v_mov_b64_e32 v[30:31], v[98:99]
	s_nop 0
	v_pk_mul_f32 v[34:35], v[28:29], v[68:69]
	v_bfe_u32 v68, v58, 16, 1
	v_add3_u32 v58, v58, v68, s89
	v_bfe_u32 v68, v59, 16, 1
	v_lshrrev_b32_e32 v58, 16, v58
	v_add3_u32 v59, v59, v68, s89
	v_and_or_b32 v58, v59, s31, v58
	v_bfe_u32 v59, v56, 16, 1
	v_add3_u32 v56, v56, v59, s89
	v_bfe_u32 v59, v57, 16, 1
	v_lshrrev_b32_e32 v56, 16, v56
	v_add3_u32 v57, v57, v59, s89
	v_and_or_b32 v59, v57, s31, v56
	v_bfe_u32 v56, v48, 16, 1
	v_add3_u32 v48, v48, v56, s89
	v_bfe_u32 v56, v49, 16, 1
	v_lshrrev_b32_e32 v48, 16, v48
	v_add3_u32 v49, v49, v56, s89
	v_and_or_b32 v48, v49, s31, v48
	v_bfe_u32 v49, v46, 16, 1
	v_add3_u32 v46, v46, v49, s89
	v_bfe_u32 v49, v47, 16, 1
	v_lshrrev_b32_e32 v46, 16, v46
	v_add3_u32 v47, v47, v49, s89
	v_and_or_b32 v49, v47, s31, v46
	v_bfe_u32 v46, v52, 16, 1
	v_add3_u32 v46, v52, v46, s89
	v_bfe_u32 v47, v53, 16, 1
	v_lshrrev_b32_e32 v46, 16, v46
	v_add3_u32 v47, v53, v47, s89
	v_and_or_b32 v46, v47, s31, v46
	v_bfe_u32 v47, v50, 16, 1
	global_store_dwordx2 v[54:55], v[48:49], off offset:512
	v_add3_u32 v47, v50, v47, s89
	v_bfe_u32 v48, v51, 16, 1
	v_lshrrev_b32_e32 v47, 16, v47
	v_add3_u32 v48, v51, v48, s89
	v_and_or_b32 v47, v48, s31, v47
	global_store_dwordx2 v[54:55], v[46:47], off offset:1024
	v_bfe_u32 v46, v34, 16, 1
	v_add3_u32 v34, v34, v46, s89
	v_bfe_u32 v46, v35, 16, 1
	v_pk_mul_f32 v[32:33], v[30:31], v[32:33]
	v_lshrrev_b32_e32 v34, 16, v34
	v_add3_u32 v35, v35, v46, s89
	v_and_or_b32 v34, v35, s31, v34
	v_bfe_u32 v35, v32, 16, 1
	v_add3_u32 v32, v32, v35, s89
	v_bfe_u32 v35, v33, 16, 1
	v_lshrrev_b32_e32 v32, 16, v32
	v_add3_u32 v33, v33, v35, s89
	v_and_or_b32 v35, v33, s31, v32
	global_store_dwordx2 v[54:55], v[58:59], off
	global_store_dwordx2 v[54:55], v[34:35], off offset:1536
	s_cbranch_scc1 .LBB0_3456
	s_waitcnt lgkmcnt(0)
	v_add_f32_e32 v32, v66, v67
	v_fmamk_f32 v32, v32, 0x3a800000, v231
	v_mul_f32_e32 v33, 0x4f800000, v32
	v_cmp_gt_f32_e32 vcc, s48, v32
	s_nop 1
	v_cndmask_b32_e32 v32, v32, v33, vcc
	v_sqrt_f32_e32 v33, v32
	s_nop 0
	v_add_u32_e32 v34, -1, v33
	v_fma_f32 v46, -v34, v33, v32
	v_add_u32_e32 v35, 1, v33
	v_cmp_ge_f32_e64 s[42:43], 0, v46
	s_nop 1
	v_cndmask_b32_e64 v34, v33, v34, s[42:43]
	v_fma_f32 v33, -v35, v33, v32
	v_cmp_lt_f32_e64 s[42:43], 0, v33
	s_nop 1
	v_cndmask_b32_e64 v33, v34, v35, s[42:43]
	v_mul_f32_e32 v34, 0x37800000, v33
	v_cndmask_b32_e32 v33, v33, v34, vcc
	v_cmp_class_f32_e32 vcc, v32, v230
	s_nop 1
	v_cndmask_b32_e32 v32, v33, v32, vcc
	v_div_scale_f32 v33, s[18:19], v32, v32, 1.0
	v_rcp_f32_e32 v34, v33
	s_nop 0
	v_fma_f32 v35, -v33, v34, 1.0
	v_fmac_f32_e32 v34, v35, v34
	v_div_scale_f32 v35, vcc, 1.0, v32, 1.0
	v_mul_f32_e32 v46, v35, v34
	v_fma_f32 v47, -v33, v46, v35
	v_fmac_f32_e32 v46, v47, v34
	v_fma_f32 v33, -v33, v46, v35
	v_div_fmas_f32 v33, v33, v34, v46
	v_div_fixup_f32 v32, v33, v32, 1.0
	v_pk_mul_f32 v[0:1], v[0:1], v[32:33] op_sel_hi:[1,0]
	v_pk_mul_f32 v[2:3], v[2:3], v[32:33] op_sel_hi:[1,0]
	v_pk_mul_f32 v[0:1], v[16:17], v[0:1]
	v_pk_mul_f32 v[2:3], v[18:19], v[2:3]
	v_bfe_u32 v18, v0, 16, 1
	v_add3_u32 v0, v0, v18, s89
	v_bfe_u32 v18, v1, 16, 1
	v_lshrrev_b32_e32 v0, 16, v0
	v_add3_u32 v1, v1, v18, s89
	v_and_or_b32 v0, v1, s31, v0
	v_bfe_u32 v1, v2, 16, 1
	v_add3_u32 v1, v2, v1, s89
	v_bfe_u32 v2, v3, 16, 1
	v_lshl_add_u64 v[16:17], s[78:79], 0, v[44:45]
	v_lshrrev_b32_e32 v1, 16, v1
	v_add3_u32 v2, v3, v2, s89
	v_pk_mul_f32 v[4:5], v[4:5], v[32:33] op_sel_hi:[1,0]
	v_and_or_b32 v1, v2, s31, v1
	v_add_co_u32_e32 v2, vcc, s14, v16
	v_pk_mul_f32 v[4:5], v[20:21], v[4:5]
	s_nop 0
	v_addc_co_u32_e32 v3, vcc, 0, v17, vcc
	global_store_dwordx2 v[2:3], v[0:1], off
	v_bfe_u32 v0, v4, 16, 1
	v_pk_mul_f32 v[6:7], v[6:7], v[32:33] op_sel_hi:[1,0]
	v_add3_u32 v0, v4, v0, s89
	v_bfe_u32 v1, v5, 16, 1
	v_pk_mul_f32 v[6:7], v[22:23], v[6:7]
	v_lshrrev_b32_e32 v0, 16, v0
	v_add3_u32 v1, v5, v1, s89
	v_and_or_b32 v0, v1, s31, v0
	v_bfe_u32 v1, v6, 16, 1
	v_add3_u32 v1, v6, v1, s89
	v_bfe_u32 v4, v7, 16, 1
	v_pk_mul_f32 v[8:9], v[8:9], v[32:33] op_sel_hi:[1,0]
	v_lshrrev_b32_e32 v1, 16, v1
	v_add3_u32 v4, v7, v4, s89
	v_pk_mul_f32 v[8:9], v[24:25], v[8:9]
	v_and_or_b32 v1, v4, s31, v1
	global_store_dwordx2 v[2:3], v[0:1], off offset:512
	v_bfe_u32 v0, v8, 16, 1
	v_pk_mul_f32 v[10:11], v[10:11], v[32:33] op_sel_hi:[1,0]
	v_add3_u32 v0, v8, v0, s89
	v_bfe_u32 v1, v9, 16, 1
	v_pk_mul_f32 v[10:11], v[26:27], v[10:11]
	v_lshrrev_b32_e32 v0, 16, v0
	v_add3_u32 v1, v9, v1, s89
	v_and_or_b32 v0, v1, s31, v0
	v_bfe_u32 v1, v10, 16, 1
	v_add3_u32 v1, v10, v1, s89
	v_bfe_u32 v4, v11, 16, 1
	v_pk_mul_f32 v[12:13], v[12:13], v[32:33] op_sel_hi:[1,0]
	v_lshrrev_b32_e32 v1, 16, v1
	v_add3_u32 v4, v11, v4, s89
	v_pk_mul_f32 v[12:13], v[28:29], v[12:13]
	v_and_or_b32 v1, v4, s31, v1
	global_store_dwordx2 v[2:3], v[0:1], off offset:1024
	v_bfe_u32 v0, v12, 16, 1
	v_pk_mul_f32 v[14:15], v[14:15], v[32:33] op_sel_hi:[1,0]
	v_add3_u32 v0, v12, v0, s89
	v_bfe_u32 v1, v13, 16, 1
	v_pk_mul_f32 v[14:15], v[30:31], v[14:15]
	v_lshrrev_b32_e32 v0, 16, v0
	v_add3_u32 v1, v13, v1, s89
	v_and_or_b32 v0, v1, s31, v0
	v_bfe_u32 v1, v14, 16, 1
	v_add3_u32 v1, v14, v1, s89
	v_bfe_u32 v4, v15, 16, 1
	v_lshrrev_b32_e32 v1, 16, v1
	v_add3_u32 v4, v15, v4, s89
	v_and_or_b32 v1, v4, s31, v1
	global_store_dwordx2 v[2:3], v[0:1], off offset:1536
	s_branch .LBB0_3456
